# DeltaNet prep segment 3: K.K^T / Q.K^T tile tail rewritten - all LDS reads batched up front (row scales as b128), A-side MFMA operands shared by both column groups, 16 masked branch blocks replaced by
# speedup vs baseline: 1.0319x; 1.0026x over previous
.LBB0_535:
	s_or_b64 exec, exec, s[10:11]
	v_and_b32_e32 v0, 0x7f, v80
	v_ashrrev_i32_e32 v47, 3, v80
	v_and_b32_e32 v2, -16, v47
	v_lshlrev_b32_e32 v59, 1, v0
	s_movk_i32 s15, 0x110
	v_add_u32_e32 v3, 0, v59
	v_mul_lo_u32 v60, v2, s15
	v_add_u32_e32 v4, v3, v60
	v_or_b32_e32 v5, 15, v47
	s_waitcnt lgkmcnt(0)
	s_barrier
	ds_read_u16 v48, v4
	ds_read_u16 v49, v4 offset:272
	ds_read_u16 v61, v4 offset:544
	ds_read_u16 v62, v4 offset:816
	ds_read_u16 v63, v4 offset:1088
	ds_read_u16 v64, v4 offset:1360
	ds_read_u16 v65, v4 offset:1632
	ds_read_u16 v66, v4 offset:1904
	v_mul_lo_u32 v67, v5, s15
	v_add_u32_e32 v5, v3, v67
	ds_read_u16 v85, v4 offset:2176
	ds_read_u16 v86, v4 offset:2448
	ds_read_u16 v87, v4 offset:2720
	ds_read_u16 v88, v4 offset:2992
	ds_read_u16 v89, v4 offset:3264
	ds_read_u16 v90, v4 offset:3536
	ds_read_u16 v91, v4 offset:3808
	ds_read_u16 v92, v5
	v_mul_u32_u24_e32 v58, 0x90, v0
	v_mul_u32_u24_e32 v0, 0x8e, v0
	v_lshlrev_b32_e32 v93, 1, v2
	s_waitcnt lgkmcnt(8)
	v_perm_b32 v7, v66, v65, s78
	v_perm_b32 v6, v64, v63, s78
	v_perm_b32 v5, v62, v61, s78
	v_perm_b32 v4, v49, v48, s78
	v_add3_u32 v0, v3, v0, v93
	s_waitcnt lgkmcnt(0)
	v_perm_b32 v17, v92, v91, s78
	v_perm_b32 v16, v90, v89, s78
	v_perm_b32 v15, v88, v87, s78
	v_perm_b32 v14, v86, v85, s78
	ds_write_b128 v0, v[4:7] offset:17408
	ds_write_b128 v0, v[14:17] offset:17424
	v_bfe_u32 v0, v80, 1, 6
	v_or_b32_e32 v0, 64, v0
	s_ashr_i32 s8, s36, 9
	v_mul_lo_u16_e32 v3, 0x87, v0
	s_ashr_i32 s9, s8, 31
	v_lshrrev_b16_e32 v3, 13, v3
	s_movk_i32 s13, 0xffc3
	s_and_b32 s10, s61, 0xfc0
	s_lshl_b64 s[8:9], s[8:9], 12
	v_mad_i32_i24 v4, v3, s13, v0
	s_or_b32 s8, s8, s10
	v_ashrrev_i32_e32 v5, 31, v4
	v_lshl_add_u64 v[4:5], s[8:9], 0, v[4:5]
	v_mov_b64_e32 v[8:9], s[24:25]
	v_mad_u64_u32 v[6:7], s[10:11], v4, s87, v[8:9]
	v_mad_i32_i24 v7, v5, s87, v7
	v_lshlrev_b32_e32 v0, 11, v3
	v_lshl_add_u64 v[4:5], v[6:7], 0, v[0:1]
	s_lshl_b32 s62, s12, 1
	v_lshlrev_b32_e32 v0, 7, v80
	v_lshl_add_u64 v[4:5], v[4:5], 0, s[62:63]
	v_and_b32_e32 v0, 0x80, v0
	v_lshl_add_u64 v[4:5], v[4:5], 0, v[0:1]
	v_lshl_add_u32 v0, v2, 2, 0
	v_ashrrev_i32_e32 v3, 31, v2
	v_add_u32_e32 v0, 0x1e900, v0
	v_lshl_add_u64 v[44:45], v[2:3], 1, v[4:5]
	ds_read_b128 v[4:7], v0
	v_lshlrev_b32_e32 v57, 16, v49
	v_lshlrev_b32_e32 v56, 16, v48
	ds_read_b128 v[14:17], v0 offset:16
	ds_read_b128 v[48:51], v0 offset:32
	ds_read_b128 v[52:55], v0 offset:48
	v_and_b32_e32 v46, 15, v80
	s_waitcnt lgkmcnt(3)
	v_pk_mul_f32 v[4:5], v[4:5], v[56:57]
	v_lshlrev_b32_e32 v57, 16, v62
	v_lshlrev_b32_e32 v56, 16, v61
	v_pk_mul_f32 v[6:7], v[6:7], v[56:57]
	v_lshlrev_b32_e32 v57, 16, v64
	v_lshlrev_b32_e32 v56, 16, v63
	s_waitcnt lgkmcnt(2)
	v_pk_mul_f32 v[14:15], v[14:15], v[56:57]
	v_lshlrev_b32_e32 v57, 16, v66
	v_lshlrev_b32_e32 v56, 16, v65
	v_pk_mul_f32 v[16:17], v[16:17], v[56:57]
	v_lshlrev_b32_e32 v57, 16, v86
	v_lshlrev_b32_e32 v56, 16, v85
	s_waitcnt lgkmcnt(1)
	v_pk_mul_f32 v[48:49], v[48:49], v[56:57]
	v_lshlrev_b32_e32 v57, 16, v88
	v_lshlrev_b32_e32 v56, 16, v87
	v_pk_mul_f32 v[50:51], v[50:51], v[56:57]
	v_lshlrev_b32_e32 v57, 16, v90
	v_lshlrev_b32_e32 v56, 16, v89
	s_waitcnt lgkmcnt(0)
	v_pk_mul_f32 v[52:53], v[52:53], v[56:57]
	v_lshlrev_b32_e32 v57, 16, v92
	v_lshlrev_b32_e32 v56, 16, v91
	v_pk_mul_f32 v[54:55], v[54:55], v[56:57]
	v_cvt_pk_bf16_f32 v4, v4, v5
	v_cvt_pk_bf16_f32 v5, v6, v7
	v_cvt_pk_bf16_f32 v6, v14, v15
	v_cvt_pk_bf16_f32 v7, v16, v17
	v_cvt_pk_bf16_f32 v14, v48, v49
	v_cvt_pk_bf16_f32 v15, v50, v51
	v_cvt_pk_bf16_f32 v16, v52, v53
	v_cvt_pk_bf16_f32 v17, v54, v55
	global_store_dwordx4 v[44:45], v[4:7], off
	global_store_dwordx4 v[44:45], v[14:17], off offset:16
	v_add_u32_e32 v0, s2, v59
	v_add_u32_e32 v3, v0, v60
	v_add_u32_e32 v0, v0, v67
	ds_read_u16 v4, v3 offset:2176
	ds_read_u16 v14, v3 offset:2448
	ds_read_u16 v5, v3 offset:2720
	ds_read_u16 v15, v3 offset:2992
	ds_read_u16 v6, v3 offset:3264
	ds_read_u16 v16, v3 offset:3536
	ds_read_u16 v7, v3 offset:3808
	ds_read_u16 v0, v0
	ds_read_u16 v44, v3
	ds_read_u16 v45, v3 offset:272
	ds_read_u16 v48, v3 offset:544
	ds_read_u16 v49, v3 offset:816
	ds_read_u16 v50, v3 offset:1088
	ds_read_u16 v51, v3 offset:1360
	ds_read_u16 v17, v3 offset:1632
	ds_read_u16 v3, v3 offset:1904
	s_waitcnt lgkmcnt(8)
	v_perm_b32 v7, v0, v7, s78
	v_perm_b32 v6, v16, v6, s78
	v_perm_b32 v5, v15, v5, s78
	v_perm_b32 v4, v14, v4, s78
	s_waitcnt lgkmcnt(0)
	v_perm_b32 v17, v3, v17, s78
	v_perm_b32 v16, v51, v50, s78
	v_perm_b32 v15, v49, v48, s78
	v_perm_b32 v14, v45, v44, s78
	v_add3_u32 v0, 0, v58, v93
	ds_write_b128 v0, v[14:17] offset:35840
	ds_write_b128 v0, v[4:7] offset:35856
	v_lshlrev_b32_e32 v0, 5, v80
	v_mul_lo_u32 v4, v47, s15
	v_and_b32_e32 v0, 0xe0, v0
	v_readlane_b32 s2, v244, 12
	v_lshl_add_u32 v3, v47, 2, 0
	v_add_u32_e32 v3, 0x1e800, v3
	v_add3_u32 v14, s2, v4, v0
	ds_read_b128 v[4:7], v14
	ds_read_b32 v44, v3
	ds_read_b128 v[14:17], v14 offset:16
	s_mov_b32 s10, 0x4325c53f
	v_mul_hi_i32 v3, v47, s10
	s_movk_i32 s14, 0xffc3
	s_waitcnt lgkmcnt(2)
	v_lshlrev_b32_e32 v48, 16, v4
	v_and_b32_e32 v49, 0xffff0000, v4
	s_waitcnt lgkmcnt(1)
	v_pk_mul_f32 v[48:49], v[44:45], v[48:49] op_sel_hi:[0,1]
	v_cvt_pk_bf16_f32 v4, v48, v49
	v_lshlrev_b32_e32 v48, 16, v5
	v_and_b32_e32 v49, 0xffff0000, v5
	v_pk_mul_f32 v[48:49], v[44:45], v[48:49] op_sel_hi:[0,1]
	v_cvt_pk_bf16_f32 v5, v48, v49
	v_lshlrev_b32_e32 v48, 16, v6
	v_and_b32_e32 v49, 0xffff0000, v6
	v_pk_mul_f32 v[48:49], v[44:45], v[48:49] op_sel_hi:[0,1]
	v_cvt_pk_bf16_f32 v6, v48, v49
	v_lshlrev_b32_e32 v48, 16, v7
	v_and_b32_e32 v49, 0xffff0000, v7
	v_pk_mul_f32 v[48:49], v[44:45], v[48:49] op_sel_hi:[0,1]
	v_cvt_pk_bf16_f32 v7, v48, v49
	s_waitcnt lgkmcnt(0)
	v_lshlrev_b32_e32 v48, 16, v14
	v_and_b32_e32 v49, 0xffff0000, v14
	v_pk_mul_f32 v[48:49], v[44:45], v[48:49] op_sel_hi:[0,1]
	v_cvt_pk_bf16_f32 v14, v48, v49
	v_lshlrev_b32_e32 v48, 16, v15
	v_and_b32_e32 v49, 0xffff0000, v15
	v_pk_mul_f32 v[48:49], v[44:45], v[48:49] op_sel_hi:[0,1]
	v_cvt_pk_bf16_f32 v15, v48, v49
	v_lshlrev_b32_e32 v48, 16, v16
	v_and_b32_e32 v49, 0xffff0000, v16
	v_pk_mul_f32 v[48:49], v[44:45], v[48:49] op_sel_hi:[0,1]
	v_cvt_pk_bf16_f32 v16, v48, v49
	v_lshlrev_b32_e32 v48, 16, v17
	v_and_b32_e32 v49, 0xffff0000, v17
	v_pk_mul_f32 v[44:45], v[44:45], v[48:49] op_sel_hi:[0,1]
	v_cvt_pk_bf16_f32 v17, v44, v45
	v_lshrrev_b32_e32 v44, 31, v3
	v_ashrrev_i32_e32 v3, 4, v3
	v_add_u32_e32 v3, v3, v44
	v_mad_i32_i24 v44, v3, s13, v47
	v_ashrrev_i32_e32 v45, 31, v44
	v_lshl_add_u64 v[44:45], s[8:9], 0, v[44:45]
	v_mad_u64_u32 v[8:9], s[10:11], v44, s87, v[8:9]
	v_lshlrev_b32_e32 v44, 10, v3
	v_mad_i32_i24 v9, v45, s87, v9
	v_ashrrev_i32_e32 v45, 31, v44
	v_lshl_add_u64 v[8:9], v[44:45], 1, v[8:9]
	v_lshl_add_u64 v[8:9], v[8:9], 0, s[62:63]
	v_lshl_add_u64 v[8:9], v[8:9], 0, v[0:1]
	global_store_dwordx4 v[8:9], v[4:7], off
	global_store_dwordx4 v[8:9], v[14:17], off offset:16
	s_nop 0
	v_lshrrev_b32_e32 v4, 1, v80
	v_and_b32_e32 v4, 24, v4
	v_lshlrev_b32_e32 v3, 5, v43
	v_lshlrev_b32_e32 v48, 1, v4
	v_bfi_b32 v4, -16, v47, v80
	v_add_u32_e32 v61, 0, v48
	v_mul_lo_u32 v4, v4, s15
	v_and_or_b32 v62, v3, 32, v46
	v_add3_u32 v51, s2, v4, v48
	v_and_b32_e32 v47, 12, v84
	v_mad_u32_u24 v44, v62, s15, v61
	v_add_u32_e32 v50, v61, v4
	v_or_b32_e32 v49, v47, v2
	ds_read_b128 v[176:179], v44
	ds_read_b128 v[100:103], v50
	ds_read_b128 v[116:119], v51
	ds_read_b128 v[180:183], v44 offset:64
	ds_read_b128 v[104:107], v50 offset:64
	ds_read_b128 v[120:123], v51 offset:64
	ds_read_b128 v[184:187], v44 offset:128
	ds_read_b128 v[108:111], v50 offset:128
	ds_read_b128 v[124:127], v51 offset:128
	ds_read_b128 v[188:191], v44 offset:192
	ds_read_b128 v[112:115], v50 offset:192
	ds_read_b128 v[128:131], v51 offset:192
	v_or_b32_e32 v85, 16, v62
	s_movk_i32 s2, 0x110
	v_lshlrev_b32_e32 v52, 2, v49
	v_mad_u32_u24 v61, v85, s2, v61
	v_add_u32_e32 v54, 0x15c00, v52
	v_add_u32_e32 v55, 0x1ea00, v52
	v_lshlrev_b32_e32 v56, 2, v62
	v_add_u32_e32 v56, 0x15d00, v56
	ds_read_b128 v[206:209], v61
	ds_read_b128 v[210:213], v61 offset:64
	s_waitcnt lgkmcnt(13)
	s_waitcnt lgkmcnt(12)
	ds_read_b128 v[214:217], v61 offset:128
	ds_read_b128 v[218:221], v61 offset:192
	v_mfma_f32_16x16x32_bf16 v[6:9], v[100:103], v[176:179], 0
	v_lshrrev_b32_e32 v53, 1, v62
	v_and_b32_e32 v53, 28, v53
	v_add_u32_e32 v53, v53, v0
	s_waitcnt lgkmcnt(13)
	ds_read_b128 v[132:135], v54 offset:256
	v_mfma_f32_16x16x32_bf16 v[2:5], v[116:119], v[176:179], 0
	v_lshl_add_u32 v53, v49, 8, v53
	v_lshlrev_b32_e32 v92, 1, v62
	v_mov_b32_e32 v93, 0
	s_waitcnt lgkmcnt(13)
	s_waitcnt lgkmcnt(12)
	ds_read_b32 v222, v56
	ds_read_b32 v224, v56 offset:64
	v_mfma_f32_16x16x32_bf16 v[6:9], v[104:107], v[180:183], v[6:9]
	s_mov_b32 s2, 0x4325c53f
	v_or_b32_e32 v57, 1, v49
	v_or_b32_e32 v59, 2, v49
	s_waitcnt lgkmcnt(13)
	ds_read_b128 v[146:149], v54
	v_mfma_f32_16x16x32_bf16 v[2:5], v[120:123], v[180:183], v[2:5]
	v_or_b32_e32 v67, 3, v49
	v_ashrrev_i32_e32 v88, 1, v49
	v_add_u32_e32 v88, 0x80, v88
	s_waitcnt lgkmcnt(7)
	ds_read_b128 v[150:153], v54 offset:768
	ds_read_b32 v223, v56 offset:512
	ds_read_b32 v225, v56 offset:576
	ds_read_b128 v[154:157], v55
	v_mfma_f32_16x16x32_bf16 v[192:195], v[100:103], v[206:209], 0
	v_mul_hi_i32 v89, v88, s2
	v_lshrrev_b32_e32 v90, 31, v89
	v_ashrrev_i32_e32 v89, 4, v89
	v_mfma_f32_16x16x32_bf16 v[196:199], v[116:119], v[206:209], 0
	v_add_u32_e32 v89, v89, v90
	v_mad_i32_i24 v14, v89, s14, v88
	v_ashrrev_i32_e32 v15, 31, v14
	v_mfma_f32_16x16x32_bf16 v[6:9], v[108:111], v[184:187], v[6:9]
	v_lshl_add_u64 v[14:15], s[8:9], 0, v[14:15]
	v_mov_b64_e32 v[86:87], s[24:25]
	v_mad_u64_u32 v[86:87], s[10:11], v14, s87, v[86:87]
	v_mfma_f32_16x16x32_bf16 v[2:5], v[124:127], v[184:187], v[2:5]
	v_mov_b32_e32 v94, v87
	v_mov_b32_e32 v95, 0
	v_mad_u64_u32 v[14:15], s[10:11], v15, s87, v[94:95]
	s_waitcnt lgkmcnt(10)
	v_mfma_f32_16x16x32_bf16 v[192:195], v[104:107], v[210:213], v[192:195]
	v_mov_b32_e32 v87, v14
	v_lshlrev_b32_e32 v14, 10, v89
	v_ashrrev_i32_e32 v15, 31, v14
	v_mfma_f32_16x16x32_bf16 v[196:199], v[120:123], v[210:213], v[196:199]
	v_lshl_add_u64 v[14:15], v[14:15], 1, v[86:87]
	v_lshl_add_u64 v[14:15], v[14:15], 0, s[62:63]
	v_lshl_add_u64 v[14:15], v[14:15], 0, v[92:93]
	v_mfma_f32_16x16x32_bf16 v[6:9], v[112:115], v[188:191], v[6:9]
	v_ashrrev_i32_e32 v88, 1, v59
	v_add_u32_e32 v88, 0x80, v88
	v_mul_hi_i32 v89, v88, s2
	v_mfma_f32_16x16x32_bf16 v[2:5], v[128:131], v[188:191], v[2:5]
	v_lshrrev_b32_e32 v90, 31, v89
	v_ashrrev_i32_e32 v89, 4, v89
	v_add_u32_e32 v89, v89, v90
	s_waitcnt lgkmcnt(9)
	v_mfma_f32_16x16x32_bf16 v[192:195], v[108:111], v[214:217], v[192:195]
	v_mad_i32_i24 v16, v89, s14, v88
	v_ashrrev_i32_e32 v17, 31, v16
	v_lshl_add_u64 v[16:17], s[8:9], 0, v[16:17]
	v_mfma_f32_16x16x32_bf16 v[196:199], v[124:127], v[214:217], v[196:199]
	v_mov_b64_e32 v[86:87], s[24:25]
	v_mad_u64_u32 v[86:87], s[10:11], v16, s87, v[86:87]
	v_mov_b32_e32 v94, v87
	s_waitcnt lgkmcnt(8)
	v_mfma_f32_16x16x32_bf16 v[192:195], v[112:115], v[218:221], v[192:195]
	v_mov_b32_e32 v95, 0
	v_mad_u64_u32 v[16:17], s[10:11], v17, s87, v[94:95]
	v_mov_b32_e32 v87, v16
	v_mfma_f32_16x16x32_bf16 v[196:199], v[128:131], v[218:221], v[196:199]
	v_lshlrev_b32_e32 v16, 10, v89
	v_ashrrev_i32_e32 v17, 31, v16
	v_lshl_add_u64 v[16:17], v[16:17], 1, v[86:87]
	v_lshl_add_u64 v[16:17], v[16:17], 0, s[62:63]
	v_lshl_add_u64 v[16:17], v[16:17], 0, v[92:93]
	s_waitcnt lgkmcnt(5)
	v_sub_f32_e32 v226, v132, v222
	v_sub_f32_e32 v227, v133, v222
	v_sub_f32_e32 v228, v134, v222
	v_sub_f32_e32 v229, v135, v222
	v_sub_f32_e32 v230, v132, v224
	v_sub_f32_e32 v231, v133, v224
	v_sub_f32_e32 v232, v134, v224
	v_sub_f32_e32 v233, v135, v224
	v_mul_f32_e32 v226, 0x3fb8aa3b, v226
	v_mul_f32_e32 v227, 0x3fb8aa3b, v227
	v_mul_f32_e32 v228, 0x3fb8aa3b, v228
	v_mul_f32_e32 v229, 0x3fb8aa3b, v229
	v_mul_f32_e32 v230, 0x3fb8aa3b, v230
	v_mul_f32_e32 v231, 0x3fb8aa3b, v231
	v_mul_f32_e32 v232, 0x3fb8aa3b, v232
	v_mul_f32_e32 v233, 0x3fb8aa3b, v233
	v_exp_f32_e32 v226, v226
	v_exp_f32_e32 v227, v227
	v_exp_f32_e32 v228, v228
	v_exp_f32_e32 v229, v229
	v_exp_f32_e32 v230, v230
	v_exp_f32_e32 v231, v231
	v_exp_f32_e32 v232, v232
	v_exp_f32_e32 v233, v233
	s_waitcnt lgkmcnt(3)
	v_mul_f32_e32 v234, v146, v150
	v_mul_f32_e32 v235, v147, v151
	v_mul_f32_e32 v236, v148, v152
	v_mul_f32_e32 v237, v149, v153
	s_waitcnt lgkmcnt(0)
	v_mul_f32_e32 v44, v223, v234
	v_mul_f32_e32 v45, v223, v154
	v_mul_f32_e32 v44, v226, v44
	v_mul_f32_e32 v45, v226, v45
	v_mul_f32_e32 v44, v6, v44
	v_mul_f32_e32 v45, v2, v45
	v_cmp_lt_i32_e32 vcc, v62, v49
	v_cvt_pk_bf16_f32 v45, v45, v45
	v_cmp_le_i32_e64 s[10:11], v62, v49
	v_cndmask_b32_e32 v44, 0, v44, vcc
	s_nop 0
	v_cndmask_b32_e64 v45, 0, v45, s[10:11]
	ds_write_b32 v53, v44 offset:54272
	global_store_short v[14:15], v45, off
	v_mul_f32_e32 v44, v223, v235
	v_mul_f32_e32 v45, v223, v155
	v_mul_f32_e32 v44, v227, v44
	v_mul_f32_e32 v45, v227, v45
	v_mul_f32_e32 v44, v7, v44
	v_mul_f32_e32 v45, v3, v45
	v_cmp_lt_i32_e32 vcc, v62, v57
	v_cvt_pk_bf16_f32 v45, v45, v45
	v_cmp_le_i32_e64 s[10:11], v62, v57
	v_cndmask_b32_e32 v44, 0, v44, vcc
	s_nop 0
	v_cndmask_b32_e64 v45, 0, v45, s[10:11]
	ds_write_b32 v53, v44 offset:54528
	global_store_short v[14:15], v45, off offset:128
	v_mul_f32_e32 v44, v223, v236
	v_mul_f32_e32 v45, v223, v156
	v_mul_f32_e32 v44, v228, v44
	v_mul_f32_e32 v45, v228, v45
	v_mul_f32_e32 v44, v8, v44
	v_mul_f32_e32 v45, v4, v45
	v_cmp_lt_i32_e32 vcc, v62, v59
	v_cvt_pk_bf16_f32 v45, v45, v45
	v_cmp_le_i32_e64 s[10:11], v62, v59
	v_cndmask_b32_e32 v44, 0, v44, vcc
	s_nop 0
	v_cndmask_b32_e64 v45, 0, v45, s[10:11]
	ds_write_b32 v53, v44 offset:54784
	global_store_short v[16:17], v45, off
	v_mul_f32_e32 v44, v223, v237
	v_mul_f32_e32 v45, v223, v157
	v_mul_f32_e32 v44, v229, v44
	v_mul_f32_e32 v45, v229, v45
	v_mul_f32_e32 v44, v9, v44
	v_mul_f32_e32 v45, v5, v45
	v_cmp_lt_i32_e32 vcc, v62, v67
	v_cvt_pk_bf16_f32 v45, v45, v45
	v_cmp_le_i32_e64 s[10:11], v62, v67
	v_cndmask_b32_e32 v44, 0, v44, vcc
	s_nop 0
	v_cndmask_b32_e64 v45, 0, v45, s[10:11]
	ds_write_b32 v53, v44 offset:55040
	global_store_short v[16:17], v45, off offset:128
	v_mul_f32_e32 v44, v225, v234
	v_mul_f32_e32 v45, v225, v154
	v_mul_f32_e32 v44, v230, v44
	v_mul_f32_e32 v45, v230, v45
	v_mul_f32_e32 v44, v192, v44
	v_mul_f32_e32 v45, v196, v45
	v_cmp_lt_i32_e32 vcc, v85, v49
	v_cvt_pk_bf16_f32 v45, v45, v45
	v_cmp_le_i32_e64 s[10:11], v85, v49
	v_cndmask_b32_e32 v44, 0, v44, vcc
	s_nop 0
	v_cndmask_b32_e64 v45, 0, v45, s[10:11]
	ds_write_b32 v53, v44 offset:54280
	global_store_short v[14:15], v45, off offset:32
	v_mul_f32_e32 v44, v225, v235
	v_mul_f32_e32 v45, v225, v155
	v_mul_f32_e32 v44, v231, v44
	v_mul_f32_e32 v45, v231, v45
	v_mul_f32_e32 v44, v193, v44
	v_mul_f32_e32 v45, v197, v45
	v_cmp_lt_i32_e32 vcc, v85, v57
	v_cvt_pk_bf16_f32 v45, v45, v45
	v_cmp_le_i32_e64 s[10:11], v85, v57
	v_cndmask_b32_e32 v44, 0, v44, vcc
	s_nop 0
	v_cndmask_b32_e64 v45, 0, v45, s[10:11]
	ds_write_b32 v53, v44 offset:54536
	global_store_short v[14:15], v45, off offset:160
	v_mul_f32_e32 v44, v225, v236
	v_mul_f32_e32 v45, v225, v156
	v_mul_f32_e32 v44, v232, v44
	v_mul_f32_e32 v45, v232, v45
	v_mul_f32_e32 v44, v194, v44
	v_mul_f32_e32 v45, v198, v45
	v_cmp_lt_i32_e32 vcc, v85, v59
	v_cvt_pk_bf16_f32 v45, v45, v45
	v_cmp_le_i32_e64 s[10:11], v85, v59
	v_cndmask_b32_e32 v44, 0, v44, vcc
	s_nop 0
	v_cndmask_b32_e64 v45, 0, v45, s[10:11]
	ds_write_b32 v53, v44 offset:54792
	global_store_short v[16:17], v45, off offset:32
	v_mul_f32_e32 v44, v225, v237
	v_mul_f32_e32 v45, v225, v157
	v_mul_f32_e32 v44, v233, v44
	v_mul_f32_e32 v45, v233, v45
	v_mul_f32_e32 v44, v195, v44
	v_mul_f32_e32 v45, v199, v45
	v_cmp_lt_i32_e32 vcc, v85, v67
	v_cvt_pk_bf16_f32 v45, v45, v45
	v_cmp_le_i32_e64 s[10:11], v85, v67
	v_cndmask_b32_e32 v44, 0, v44, vcc
	s_nop 0
	v_cndmask_b32_e64 v45, 0, v45, s[10:11]
	ds_write_b32 v53, v44 offset:55048
	global_store_short v[16:17], v45, off offset:160
	s_add_i32 s2, s36, s50
	s_cmpk_gt_i32 s2, 0xfff
	s_cselect_b64 s[38:39], -1, 0
	s_cmpk_lt_i32 s2, 0x1000
	s_mov_b64 s[8:9], -1
	s_waitcnt lgkmcnt(0)
	s_barrier
	s_cbranch_scc1 .LBB0_569
	s_add_i32 s10, s61, s51
	s_mov_b64 s[8:9], 0
